# speedup vs baseline: 1.0008x; 1.0008x over previous
; template <int DH, int MODE>
; __device__ void attn_item(const Params& p, int layer, int b, int blk, int head, char* smem) {
;     ...
;     V_SCATTER_(vr0, 0);
;     V_SCATTER_(vr1, 1);
;     if (KCH > 2) {
;       V_SCATTER_(vr2, 2);
;       V_SCATTER_(vr3, 3);
;     }
;     KV_LOAD_(it + 1);
;     if (!wskip) {
;       float4* s4 = reinterpret_cast<float4*>(Sf + row * SSTR + half * 32);
;       char* prow = Pb + half * 8192 + row * 64;
;       if (MODE == 0) {
;         const int kjb = kj0 + half * 32;
;         float tmax = -1e30f;
; #pragma unroll
;         for (int c = 0; c < 8; ++c) {
;           float4 v = s4[c];
;           float e[4] = {v.x, v.y, v.z, v.w};
; #pragma unroll
;           for (int k = 0; k < 4; ++k) {
;             int kj = kjb + c * 4 + k;
;             bool valid = (kj > row) && (kj <= row + 128);
;             tmax = valid ? fmaxf(tmax, e[k]) : tmax;
;           }
;         }
;         tmax = fmaxf(tmax, __shfl_xor(tmax, 1));
;         float m_new = fmaxf(m_run, tmax);
;         float alpha = __builtin_amdgcn_exp2f(m_run - m_new);
.LBB0_166:
	s_or_b64 exec, exec, s[6:7]
	s_add_i32 s86, s86, 1
	s_min_i32 s6, s86, s84
	s_add_i32 s6, s6, s83
	s_lshl_b32 s6, s6, 6
	s_add_i32 s6, s6, s85
	s_ashr_i32 s7, s6, 31
	s_add_u32 s6, s6, s81
	s_addc_u32 s7, s7, 0
	s_waitcnt lgkmcnt(0)
	s_barrier
	ds_write_b16 v96, v48
	ds_write_b16_d16_hi v96, v48 offset:64
	ds_write_b16 v96, v49 offset:128
	ds_write_b16_d16_hi v96, v49 offset:192
	ds_write_b16 v96, v50 offset:256
	ds_write_b16_d16_hi v96, v50 offset:320
	ds_write_b16 v96, v51 offset:384
	ds_write_b16_d16_hi v96, v51 offset:448
	s_waitcnt vmcnt(0)
	ds_write_b16 v96, v52 offset:2048
	ds_write_b16_d16_hi v96, v52 offset:2112
	ds_write_b16 v96, v53 offset:2176
	ds_write_b16_d16_hi v96, v53 offset:2240
	ds_write_b16 v96, v54 offset:2304
	ds_write_b16_d16_hi v96, v54 offset:2368
	ds_write_b16 v96, v55 offset:2432
	ds_write_b16_d16_hi v96, v55 offset:2496
	v_lshl_add_u64 v[48:49], s[6:7], 0, v[66:67]
	v_mad_u64_u32 v[52:53], s[10:11], v48, s55, v[76:77]
	v_or_b32_e32 v48, s6, v72
	v_mad_i32_i24 v53, v49, s55, v53
	v_mad_u64_u32 v[54:55], s[10:11], v48, s55, v[78:79]
	v_add_co_u32_e32 v48, vcc, 0x4c000, v52
	v_mad_i32_i24 v55, s7, v160, v55
	s_nop 0
	v_addc_co_u32_e32 v49, vcc, 0, v53, vcc
	global_load_dwordx4 v[60:63], v[48:49], off
	s_nop 0
	global_load_dwordx4 v[48:51], v[54:55], off
	global_load_dwordx4 v[56:59], v[52:53], off
	s_nop 0
	global_load_dwordx4 v[52:55], v[54:55], off offset:64
	s_and_saveexec_b64 s[52:53], s[50:51]
	s_cbranch_execz .LBB0_188
	v_or_b32_e32 v101, s8, v89
	s_movk_i32 s91, 0x80
	ds_read_b128 v[164:167], v90 offset:16384
	ds_read_b128 v[168:171], v90 offset:16400
	ds_read_b128 v[172:175], v90 offset:16416
	ds_read_b128 v[176:179], v90 offset:16432
	ds_read_b128 v[180:183], v90 offset:16448
	ds_read_b128 v[184:187], v90 offset:16464
	ds_read_b128 v[188:191], v90 offset:16480
	ds_read_b128 v[192:195], v90 offset:16496
	v_sub_u32_e32 v102, v80, v101
	v_mov_b32_e32 v83, 0xf149f2ca
	v_add_u32_e32 v103, -31, v102
	v_cmp_gt_u32_e32 vcc, 0x61, v103
	s_cmp_eq_u64 vcc, exec
	s_cbranch_scc1 .Lswa_tfast_3
	v_mov_b32_e32 v161, v102
	v_add_u32_e32 v162, -1, v102
	v_add_u32_e32 v163, -2, v102
	v_cmp_gt_u32_e32 vcc, s91, v161
	v_cmp_gt_u32_e64 s[92:93], s91, v162
	v_cmp_gt_u32_e64 s[94:95], s91, v163
	s_waitcnt lgkmcnt(7)
	v_cndmask_b32_e32 v200, v83, v164, vcc
	v_cndmask_b32_e64 v201, v83, v165, s[92:93]
	v_cndmask_b32_e64 v202, v83, v166, s[94:95]
	v_add_u32_e32 v161, -3, v102
	v_add_u32_e32 v162, -4, v102
	v_add_u32_e32 v163, -5, v102
	v_cmp_gt_u32_e32 vcc, s91, v161
	v_cmp_gt_u32_e64 s[92:93], s91, v162
	v_cmp_gt_u32_e64 s[94:95], s91, v163
	s_waitcnt lgkmcnt(6)
	v_cndmask_b32_e32 v203, v83, v167, vcc
	v_cndmask_b32_e64 v204, v83, v168, s[92:93]
	v_cndmask_b32_e64 v205, v83, v169, s[94:95]
	v_add_u32_e32 v161, -6, v102
	v_add_u32_e32 v162, -7, v102
	v_add_u32_e32 v163, -8, v102
	v_cmp_gt_u32_e32 vcc, s91, v161
	v_cmp_gt_u32_e64 s[92:93], s91, v162
	v_cmp_gt_u32_e64 s[94:95], s91, v163
	s_waitcnt lgkmcnt(5)
	v_cndmask_b32_e32 v206, v83, v170, vcc
	v_cndmask_b32_e64 v207, v83, v171, s[92:93]
	v_cndmask_b32_e64 v208, v83, v172, s[94:95]
	v_add_u32_e32 v161, -9, v102
	v_add_u32_e32 v162, -10, v102
	v_add_u32_e32 v163, -11, v102
	v_cmp_gt_u32_e32 vcc, s91, v161
	v_cmp_gt_u32_e64 s[92:93], s91, v162
	v_cmp_gt_u32_e64 s[94:95], s91, v163
	v_cndmask_b32_e32 v209, v83, v173, vcc
	v_cndmask_b32_e64 v210, v83, v174, s[92:93]
	v_cndmask_b32_e64 v211, v83, v175, s[94:95]
	v_add_u32_e32 v161, -12, v102
	v_add_u32_e32 v162, -13, v102
	v_add_u32_e32 v163, -14, v102
	v_cmp_gt_u32_e32 vcc, s91, v161
	v_cmp_gt_u32_e64 s[92:93], s91, v162
	v_cmp_gt_u32_e64 s[94:95], s91, v163
	s_waitcnt lgkmcnt(4)
	v_cndmask_b32_e32 v212, v83, v176, vcc
	v_cndmask_b32_e64 v213, v83, v177, s[92:93]
	v_cndmask_b32_e64 v214, v83, v178, s[94:95]
	v_add_u32_e32 v161, -15, v102
	v_add_u32_e32 v162, -16, v102
	v_add_u32_e32 v163, 0xffffffef, v102
	v_cmp_gt_u32_e32 vcc, s91, v161
	v_cmp_gt_u32_e64 s[92:93], s91, v162
	v_cmp_gt_u32_e64 s[94:95], s91, v163
	s_waitcnt lgkmcnt(3)
	v_cndmask_b32_e32 v215, v83, v179, vcc
	v_cndmask_b32_e64 v216, v83, v180, s[92:93]
	v_cndmask_b32_e64 v217, v83, v181, s[94:95]
	v_add_u32_e32 v161, 0xffffffee, v102
	v_add_u32_e32 v162, 0xffffffed, v102
	v_add_u32_e32 v163, 0xffffffec, v102
	v_cmp_gt_u32_e32 vcc, s91, v161
	v_cmp_gt_u32_e64 s[92:93], s91, v162
	v_cmp_gt_u32_e64 s[94:95], s91, v163
	s_waitcnt lgkmcnt(2)
	v_cndmask_b32_e32 v218, v83, v182, vcc
	v_cndmask_b32_e64 v219, v83, v183, s[92:93]
	v_cndmask_b32_e64 v220, v83, v184, s[94:95]
	v_add_u32_e32 v161, 0xffffffeb, v102
	v_add_u32_e32 v162, 0xffffffea, v102
	v_add_u32_e32 v163, 0xffffffe9, v102
	v_cmp_gt_u32_e32 vcc, s91, v161
	v_cmp_gt_u32_e64 s[92:93], s91, v162
	v_cmp_gt_u32_e64 s[94:95], s91, v163
	v_cndmask_b32_e32 v221, v83, v185, vcc
	v_cndmask_b32_e64 v222, v83, v186, s[92:93]
	v_cndmask_b32_e64 v223, v83, v187, s[94:95]
	v_add_u32_e32 v161, 0xffffffe8, v102
	v_add_u32_e32 v162, 0xffffffe7, v102
	v_add_u32_e32 v163, 0xffffffe6, v102
	v_cmp_gt_u32_e32 vcc, s91, v161
	v_cmp_gt_u32_e64 s[92:93], s91, v162
	v_cmp_gt_u32_e64 s[94:95], s91, v163
	s_waitcnt lgkmcnt(1)
	v_cndmask_b32_e32 v224, v83, v188, vcc
	v_cndmask_b32_e64 v225, v83, v189, s[92:93]
	v_cndmask_b32_e64 v226, v83, v190, s[94:95]
	v_add_u32_e32 v161, 0xffffffe5, v102
	v_add_u32_e32 v162, 0xffffffe4, v102
	v_add_u32_e32 v163, 0xffffffe3, v102
	v_cmp_gt_u32_e32 vcc, s91, v161
	v_cmp_gt_u32_e64 s[92:93], s91, v162
	v_cmp_gt_u32_e64 s[94:95], s91, v163
	s_waitcnt lgkmcnt(0)
	v_cndmask_b32_e32 v227, v83, v191, vcc
	v_cndmask_b32_e64 v228, v83, v192, s[92:93]
	v_cndmask_b32_e64 v229, v83, v193, s[94:95]
	v_add_u32_e32 v161, 0xffffffe2, v102
	v_add_u32_e32 v162, 0xffffffe1, v102
	v_cmp_gt_u32_e32 vcc, s91, v161
	v_cmp_gt_u32_e64 s[92:93], s91, v162
	s_nop 0
	v_cndmask_b32_e32 v230, v83, v194, vcc
	v_cndmask_b32_e64 v231, v83, v195, s[92:93]
	v_max3_f32 v200, v200, v201, v202
	v_max3_f32 v203, v203, v204, v205
	v_max3_f32 v206, v206, v207, v208
	v_max3_f32 v209, v209, v210, v211
	v_max3_f32 v212, v212, v213, v214
	v_max3_f32 v215, v215, v216, v217
	v_max3_f32 v218, v218, v219, v220
	v_max3_f32 v221, v221, v222, v223
	v_max3_f32 v224, v224, v225, v226
	v_max3_f32 v227, v227, v228, v229
	v_max_f32_e32 v230, v230, v231
	v_max3_f32 v200, v200, v203, v206
	v_max3_f32 v209, v209, v212, v215
	v_max3_f32 v218, v218, v221, v224
	v_max_f32_e32 v227, v227, v230
	v_max3_f32 v200, v200, v209, v218
	v_max_f32_e32 v200, v200, v227
	v_mov_b32_e32 v82, v200
	s_branch .Lswa_tdone_3
; template <int DH, int MODE>
; __device__ void attn_item(const Params& p, int layer, int b, int blk, int head, char* smem) {
;     ...
;         float tmax = -1e30f;
; #pragma unroll
;         for (int c = 0; c < 8; ++c) {
;           float4 v = s4[c];
;           float e[4] = {v.x, v.y, v.z, v.w};
; #pragma unroll
;           for (int k = 0; k < 4; ++k) {
;             int kj = kjb + c * 4 + k;
;             bool valid = (kj > row) && (kj <= row + 128);
;             tmax = valid ? fmaxf(tmax, e[k]) : tmax;
;           }
;         }
;         tmax = fmaxf(tmax, __shfl_xor(tmax, 1));
;         float m_new = fmaxf(m_run, tmax);
;         float alpha = __builtin_amdgcn_exp2f(m_run - m_new);
;         float psum = 0.f;
; #pragma unroll 2
;         for (int s8 = 0; s8 < 4; ++s8) {
;           float4 va = s4[2 * s8], vb = s4[2 * s8 + 1];
;           float e[8] = {va.x, va.y, va.z, va.w, vb.x, vb.y, vb.z, vb.w};
;           float pv[8];
; #pragma unroll
;           for (int k = 0; k < 8; ++k) {
;             int kj = kjb + s8 * 8 + k;
;             bool valid = (kj > row) && (kj <= row + 128);
;             float pe = valid ? __builtin_amdgcn_exp2f(e[k] - m_new) : 0.f;
;             pv[k] = pe;
;             psum += pe;
;           }
.Lswa_tfast_3:
	s_waitcnt lgkmcnt(0)
	v_max3_f32 v200, v164, v165, v166
	v_max3_f32 v201, v167, v168, v169
	v_max3_f32 v202, v170, v171, v172
	v_max3_f32 v203, v173, v174, v175
	v_max3_f32 v204, v176, v177, v178
	v_max3_f32 v205, v179, v180, v181
	v_max3_f32 v206, v182, v183, v184
	v_max3_f32 v207, v185, v186, v187
	v_max3_f32 v208, v188, v189, v190
	v_max3_f32 v209, v191, v192, v193
	v_max3_f32 v210, v194, v195, v83
	v_max3_f32 v200, v200, v201, v202
	v_max3_f32 v203, v203, v204, v205
	v_max3_f32 v206, v206, v207, v208
	v_max_f32_e32 v209, v209, v210
	v_max3_f32 v200, v200, v203, v206
	v_max_f32_e32 v200, v200, v209
	v_mov_b32_e32 v82, v200
.Lswa_tdone_3:
	v_cmp_lt_i32_e32 vcc, v157, v158
	s_mov_b32 s87, 0
	v_mov_b32_e32 v103, 0
	v_cndmask_b32_e32 v83, v156, v157, vcc
	v_lshlrev_b32_e32 v83, 2, v83
	ds_bpermute_b32 v101, v83, v82
	v_mov_b32_e32 v102, v91
	s_waitcnt lgkmcnt(0)
	v_max3_f32 v82, v87, v82, v101
	v_mov_b32_e32 v101, v93
	s_movk_i32 s91, 0x80
	v_sub_u32_e32 v112, v80, v92
	v_add_u32_e32 v113, -31, v112
	v_cmp_gt_u32_e32 vcc, 0x61, v113
	s_cmp_eq_u64 vcc, exec
	s_cbranch_scc1 .Lswa_pfast_3
	v_sub_f32_e32 v164, v164, v82
	v_sub_f32_e32 v165, v165, v82
	v_sub_f32_e32 v166, v166, v82
	v_exp_f32_e32 v164, v164
	v_exp_f32_e32 v165, v165
	v_exp_f32_e32 v166, v166
	v_mov_b32_e32 v196, v112
	v_add_u32_e32 v197, -1, v112
	v_add_u32_e32 v198, -2, v112
	v_cmp_gt_u32_e32 vcc, s91, v196
	v_cmp_gt_u32_e64 s[92:93], s91, v197
	v_cmp_gt_u32_e64 s[94:95], s91, v198
	v_cndmask_b32_e32 v164, 0, v164, vcc
	v_cndmask_b32_e64 v165, 0, v165, s[92:93]
	v_cndmask_b32_e64 v166, 0, v166, s[94:95]
	v_add_f32_e32 v103, v103, v164
	v_add_f32_e32 v103, v103, v165
	v_add_f32_e32 v103, v103, v166
	v_sub_f32_e32 v167, v167, v82
	v_sub_f32_e32 v168, v168, v82
	v_sub_f32_e32 v169, v169, v82
	v_exp_f32_e32 v167, v167
	v_exp_f32_e32 v168, v168
	v_exp_f32_e32 v169, v169
	v_add_u32_e32 v196, -3, v112
	v_add_u32_e32 v197, -4, v112
	v_add_u32_e32 v198, -5, v112
	v_cmp_gt_u32_e32 vcc, s91, v196
	v_cmp_gt_u32_e64 s[92:93], s91, v197
	v_cmp_gt_u32_e64 s[94:95], s91, v198
	v_cndmask_b32_e32 v167, 0, v167, vcc
	v_cndmask_b32_e64 v168, 0, v168, s[92:93]
	v_cndmask_b32_e64 v169, 0, v169, s[94:95]
	v_add_f32_e32 v103, v103, v167
	v_add_f32_e32 v103, v103, v168
	v_add_f32_e32 v103, v103, v169
	v_sub_f32_e32 v170, v170, v82
	v_sub_f32_e32 v171, v171, v82
	v_sub_f32_e32 v172, v172, v82
	v_exp_f32_e32 v170, v170
	v_exp_f32_e32 v171, v171
	v_exp_f32_e32 v172, v172
	v_add_u32_e32 v196, -6, v112
	v_add_u32_e32 v197, -7, v112
	v_add_u32_e32 v198, -8, v112
	v_cmp_gt_u32_e32 vcc, s91, v196
	v_cmp_gt_u32_e64 s[92:93], s91, v197
	v_cmp_gt_u32_e64 s[94:95], s91, v198
	v_cndmask_b32_e32 v170, 0, v170, vcc
	v_cndmask_b32_e64 v171, 0, v171, s[92:93]
	v_cndmask_b32_e64 v172, 0, v172, s[94:95]
	v_add_f32_e32 v103, v103, v170
	v_add_f32_e32 v103, v103, v171
	v_add_f32_e32 v103, v103, v172
	v_sub_f32_e32 v173, v173, v82
	v_sub_f32_e32 v174, v174, v82
	v_sub_f32_e32 v175, v175, v82
	v_exp_f32_e32 v173, v173
	v_exp_f32_e32 v174, v174
	v_exp_f32_e32 v175, v175
	v_add_u32_e32 v196, -9, v112
	v_add_u32_e32 v197, -10, v112
	v_add_u32_e32 v198, -11, v112
	v_cmp_gt_u32_e32 vcc, s91, v196
	v_cmp_gt_u32_e64 s[92:93], s91, v197
	v_cmp_gt_u32_e64 s[94:95], s91, v198
	v_cndmask_b32_e32 v173, 0, v173, vcc
	v_cndmask_b32_e64 v174, 0, v174, s[92:93]
	v_cndmask_b32_e64 v175, 0, v175, s[94:95]
	v_add_f32_e32 v103, v103, v173
	v_add_f32_e32 v103, v103, v174
	v_add_f32_e32 v103, v103, v175
	v_sub_f32_e32 v176, v176, v82
	v_sub_f32_e32 v177, v177, v82
	v_sub_f32_e32 v178, v178, v82
	v_exp_f32_e32 v176, v176
	v_exp_f32_e32 v177, v177
	v_exp_f32_e32 v178, v178
	v_add_u32_e32 v196, -12, v112
	v_add_u32_e32 v197, -13, v112
	v_add_u32_e32 v198, -14, v112
	v_cmp_gt_u32_e32 vcc, s91, v196
	v_cmp_gt_u32_e64 s[92:93], s91, v197
	v_cmp_gt_u32_e64 s[94:95], s91, v198
	v_cndmask_b32_e32 v176, 0, v176, vcc
	v_cndmask_b32_e64 v177, 0, v177, s[92:93]
	v_cndmask_b32_e64 v178, 0, v178, s[94:95]
	v_add_f32_e32 v103, v103, v176
	v_add_f32_e32 v103, v103, v177
	v_add_f32_e32 v103, v103, v178
	v_sub_f32_e32 v179, v179, v82
	v_sub_f32_e32 v180, v180, v82
	v_sub_f32_e32 v181, v181, v82
	v_exp_f32_e32 v179, v179
	v_exp_f32_e32 v180, v180
	v_exp_f32_e32 v181, v181
	v_add_u32_e32 v196, -15, v112
	v_add_u32_e32 v197, -16, v112
	v_add_u32_e32 v198, 0xffffffef, v112
	v_cmp_gt_u32_e32 vcc, s91, v196
	v_cmp_gt_u32_e64 s[92:93], s91, v197
	v_cmp_gt_u32_e64 s[94:95], s91, v198
	v_cndmask_b32_e32 v179, 0, v179, vcc
	v_cndmask_b32_e64 v180, 0, v180, s[92:93]
	v_cndmask_b32_e64 v181, 0, v181, s[94:95]
	v_add_f32_e32 v103, v103, v179
	v_add_f32_e32 v103, v103, v180
	v_add_f32_e32 v103, v103, v181
	v_sub_f32_e32 v182, v182, v82
	v_sub_f32_e32 v183, v183, v82
	v_sub_f32_e32 v184, v184, v82
	v_exp_f32_e32 v182, v182
	v_exp_f32_e32 v183, v183
	v_exp_f32_e32 v184, v184
	v_add_u32_e32 v196, 0xffffffee, v112
	v_add_u32_e32 v197, 0xffffffed, v112
	v_add_u32_e32 v198, 0xffffffec, v112
	v_cmp_gt_u32_e32 vcc, s91, v196
	v_cmp_gt_u32_e64 s[92:93], s91, v197
	v_cmp_gt_u32_e64 s[94:95], s91, v198
	v_cndmask_b32_e32 v182, 0, v182, vcc
	v_cndmask_b32_e64 v183, 0, v183, s[92:93]
	v_cndmask_b32_e64 v184, 0, v184, s[94:95]
	v_add_f32_e32 v103, v103, v182
	v_add_f32_e32 v103, v103, v183
	v_add_f32_e32 v103, v103, v184
	v_sub_f32_e32 v185, v185, v82
	v_sub_f32_e32 v186, v186, v82
	v_sub_f32_e32 v187, v187, v82
	v_exp_f32_e32 v185, v185
	v_exp_f32_e32 v186, v186
	v_exp_f32_e32 v187, v187
	v_add_u32_e32 v196, 0xffffffeb, v112
	v_add_u32_e32 v197, 0xffffffea, v112
	v_add_u32_e32 v198, 0xffffffe9, v112
	v_cmp_gt_u32_e32 vcc, s91, v196
	v_cmp_gt_u32_e64 s[92:93], s91, v197
; __device__ __forceinline__ unsigned pack2(float a, float b) { return (unsigned)f2bf(a) | ((unsigned)f2bf(b) << 16); }
; template <int DH, int MODE>
; __device__ void attn_item(const Params& p, int layer, int b, int blk, int head, char* smem) {
;     ...
; #pragma unroll 2
;         for (int s8 = 0; s8 < 4; ++s8) {
;           float4 va = s4[2 * s8], vb = s4[2 * s8 + 1];
;           float e[8] = {va.x, va.y, va.z, va.w, vb.x, vb.y, vb.z, vb.w};
;           float pv[8];
; #pragma unroll
;           for (int k = 0; k < 8; ++k) {
;             int kj = kjb + s8 * 8 + k;
;             bool valid = (kj > row) && (kj <= row + 128);
;             float pe = valid ? __builtin_amdgcn_exp2f(e[k] - m_new) : 0.f;
;             pv[k] = pe;
;             psum += pe;
;           }
;           uint4 ov;
;           ov.x = pack2(pv[0], pv[1]); ov.y = pack2(pv[2], pv[3]);
;           ov.z = pack2(pv[4], pv[5]); ov.w = pack2(pv[6], pv[7]);
;           *reinterpret_cast<uint4*>(prow + s8 * 16) = ov;
;         }
	v_cmp_gt_u32_e64 s[94:95], s91, v198
	v_cndmask_b32_e32 v185, 0, v185, vcc
	v_cndmask_b32_e64 v186, 0, v186, s[92:93]
	v_cndmask_b32_e64 v187, 0, v187, s[94:95]
	v_add_f32_e32 v103, v103, v185
	v_add_f32_e32 v103, v103, v186
	v_add_f32_e32 v103, v103, v187
	v_sub_f32_e32 v188, v188, v82
	v_sub_f32_e32 v189, v189, v82
	v_sub_f32_e32 v190, v190, v82
	v_exp_f32_e32 v188, v188
	v_exp_f32_e32 v189, v189
	v_exp_f32_e32 v190, v190
	v_add_u32_e32 v196, 0xffffffe8, v112
	v_add_u32_e32 v197, 0xffffffe7, v112
	v_add_u32_e32 v198, 0xffffffe6, v112
	v_cmp_gt_u32_e32 vcc, s91, v196
	v_cmp_gt_u32_e64 s[92:93], s91, v197
	v_cmp_gt_u32_e64 s[94:95], s91, v198
	v_cndmask_b32_e32 v188, 0, v188, vcc
	v_cndmask_b32_e64 v189, 0, v189, s[92:93]
	v_cndmask_b32_e64 v190, 0, v190, s[94:95]
	v_add_f32_e32 v103, v103, v188
	v_add_f32_e32 v103, v103, v189
	v_add_f32_e32 v103, v103, v190
	v_sub_f32_e32 v191, v191, v82
	v_sub_f32_e32 v192, v192, v82
	v_sub_f32_e32 v193, v193, v82
	v_exp_f32_e32 v191, v191
	v_exp_f32_e32 v192, v192
	v_exp_f32_e32 v193, v193
	v_add_u32_e32 v196, 0xffffffe5, v112
	v_add_u32_e32 v197, 0xffffffe4, v112
	v_add_u32_e32 v198, 0xffffffe3, v112
	v_cmp_gt_u32_e32 vcc, s91, v196
	v_cmp_gt_u32_e64 s[92:93], s91, v197
	v_cmp_gt_u32_e64 s[94:95], s91, v198
	v_cndmask_b32_e32 v191, 0, v191, vcc
	v_cndmask_b32_e64 v192, 0, v192, s[92:93]
	v_cndmask_b32_e64 v193, 0, v193, s[94:95]
	v_add_f32_e32 v103, v103, v191
	v_add_f32_e32 v103, v103, v192
	v_add_f32_e32 v103, v103, v193
	v_sub_f32_e32 v194, v194, v82
	v_sub_f32_e32 v195, v195, v82
	v_exp_f32_e32 v194, v194
	v_exp_f32_e32 v195, v195
	v_add_u32_e32 v196, 0xffffffe2, v112
	v_add_u32_e32 v197, 0xffffffe1, v112
	v_cmp_gt_u32_e32 vcc, s91, v196
	v_cmp_gt_u32_e64 s[92:93], s91, v197
	s_nop 0
	v_cndmask_b32_e32 v194, 0, v194, vcc
	v_cndmask_b32_e64 v195, 0, v195, s[92:93]
	v_add_f32_e32 v103, v103, v194
	v_add_f32_e32 v103, v103, v195
	v_cvt_pk_bf16_f32 v104, v164, v165
	v_cvt_pk_bf16_f32 v105, v166, v167
	v_cvt_pk_bf16_f32 v106, v168, v169
	v_cvt_pk_bf16_f32 v107, v170, v171
	ds_write_b128 v101, v[104:107]
	s_nop 0
	v_cvt_pk_bf16_f32 v104, v172, v173
	v_cvt_pk_bf16_f32 v105, v174, v175
	v_cvt_pk_bf16_f32 v106, v176, v177
	v_cvt_pk_bf16_f32 v107, v178, v179
	ds_write_b128 v101, v[104:107] offset:16
	s_nop 0
	v_cvt_pk_bf16_f32 v104, v180, v181
	v_cvt_pk_bf16_f32 v105, v182, v183
	v_cvt_pk_bf16_f32 v106, v184, v185
	v_cvt_pk_bf16_f32 v107, v186, v187
	ds_write_b128 v101, v[104:107] offset:32
	s_nop 0
	v_cvt_pk_bf16_f32 v104, v188, v189
	v_cvt_pk_bf16_f32 v105, v190, v191
	v_cvt_pk_bf16_f32 v106, v192, v193
	v_cvt_pk_bf16_f32 v107, v194, v195
	ds_write_b128 v101, v[104:107] offset:48
	s_branch .Lswa_pdone_3
.Lswa_pfast_3:
	v_sub_f32_e32 v164, v164, v82
	v_sub_f32_e32 v165, v165, v82
	v_sub_f32_e32 v166, v166, v82
	v_sub_f32_e32 v167, v167, v82
	v_exp_f32_e32 v164, v164
	v_exp_f32_e32 v165, v165
	v_exp_f32_e32 v166, v166
	v_exp_f32_e32 v167, v167
	v_add_f32_e32 v103, v103, v164
	v_add_f32_e32 v103, v103, v165
	v_add_f32_e32 v103, v103, v166
	v_add_f32_e32 v103, v103, v167
	v_sub_f32_e32 v168, v168, v82
	v_sub_f32_e32 v169, v169, v82
	v_sub_f32_e32 v170, v170, v82
	v_sub_f32_e32 v171, v171, v82
	v_exp_f32_e32 v168, v168
	v_exp_f32_e32 v169, v169
	v_exp_f32_e32 v170, v170
	v_exp_f32_e32 v171, v171
	v_add_f32_e32 v103, v103, v168
	v_add_f32_e32 v103, v103, v169
	v_add_f32_e32 v103, v103, v170
	v_add_f32_e32 v103, v103, v171
	v_sub_f32_e32 v172, v172, v82
	v_sub_f32_e32 v173, v173, v82
	v_sub_f32_e32 v174, v174, v82
	v_sub_f32_e32 v175, v175, v82
	v_exp_f32_e32 v172, v172
	v_exp_f32_e32 v173, v173
	v_exp_f32_e32 v174, v174
	v_exp_f32_e32 v175, v175
	v_add_f32_e32 v103, v103, v172
	v_add_f32_e32 v103, v103, v173
	v_add_f32_e32 v103, v103, v174
	v_add_f32_e32 v103, v103, v175
	v_sub_f32_e32 v176, v176, v82
	v_sub_f32_e32 v177, v177, v82
	v_sub_f32_e32 v178, v178, v82
	v_sub_f32_e32 v179, v179, v82
	v_exp_f32_e32 v176, v176
	v_exp_f32_e32 v177, v177
	v_exp_f32_e32 v178, v178
	v_exp_f32_e32 v179, v179
	v_add_f32_e32 v103, v103, v176
	v_add_f32_e32 v103, v103, v177
	v_add_f32_e32 v103, v103, v178
	v_add_f32_e32 v103, v103, v179
	v_sub_f32_e32 v180, v180, v82
	v_sub_f32_e32 v181, v181, v82
	v_sub_f32_e32 v182, v182, v82
	v_sub_f32_e32 v183, v183, v82
	v_exp_f32_e32 v180, v180
	v_exp_f32_e32 v181, v181
	v_exp_f32_e32 v182, v182
	v_exp_f32_e32 v183, v183
	v_add_f32_e32 v103, v103, v180
	v_add_f32_e32 v103, v103, v181
	v_add_f32_e32 v103, v103, v182
	v_add_f32_e32 v103, v103, v183
	v_sub_f32_e32 v184, v184, v82
	v_sub_f32_e32 v185, v185, v82
	v_sub_f32_e32 v186, v186, v82
	v_sub_f32_e32 v187, v187, v82
	v_exp_f32_e32 v184, v184
	v_exp_f32_e32 v185, v185
	v_exp_f32_e32 v186, v186
	v_exp_f32_e32 v187, v187
	v_add_f32_e32 v103, v103, v184
	v_add_f32_e32 v103, v103, v185
	v_add_f32_e32 v103, v103, v186
	v_add_f32_e32 v103, v103, v187
	v_sub_f32_e32 v188, v188, v82
	v_sub_f32_e32 v189, v189, v82
	v_sub_f32_e32 v190, v190, v82
	v_sub_f32_e32 v191, v191, v82
	v_exp_f32_e32 v188, v188
	v_exp_f32_e32 v189, v189
	v_exp_f32_e32 v190, v190
	v_exp_f32_e32 v191, v191
	v_add_f32_e32 v103, v103, v188
	v_add_f32_e32 v103, v103, v189
	v_add_f32_e32 v103, v103, v190
	v_add_f32_e32 v103, v103, v191
	v_sub_f32_e32 v192, v192, v82
	v_sub_f32_e32 v193, v193, v82
	v_sub_f32_e32 v194, v194, v82
	v_sub_f32_e32 v195, v195, v82
	v_exp_f32_e32 v192, v192
	v_exp_f32_e32 v193, v193
	v_exp_f32_e32 v194, v194
	v_exp_f32_e32 v195, v195
	v_add_f32_e32 v103, v103, v192
	v_add_f32_e32 v103, v103, v193
	v_add_f32_e32 v103, v103, v194
	v_add_f32_e32 v103, v103, v195
	v_cvt_pk_bf16_f32 v104, v164, v165
	v_cvt_pk_bf16_f32 v105, v166, v167
	v_cvt_pk_bf16_f32 v106, v168, v169
	v_cvt_pk_bf16_f32 v107, v170, v171
	ds_write_b128 v101, v[104:107]
	s_nop 0
	v_cvt_pk_bf16_f32 v104, v172, v173
	v_cvt_pk_bf16_f32 v105, v174, v175
	v_cvt_pk_bf16_f32 v106, v176, v177
	v_cvt_pk_bf16_f32 v107, v178, v179
	ds_write_b128 v101, v[104:107] offset:16
	s_nop 0
	v_cvt_pk_bf16_f32 v104, v180, v181
	v_cvt_pk_bf16_f32 v105, v182, v183
	v_cvt_pk_bf16_f32 v106, v184, v185
	v_cvt_pk_bf16_f32 v107, v186, v187
	ds_write_b128 v101, v[104:107] offset:32
	s_nop 0
	v_cvt_pk_bf16_f32 v104, v188, v189
	v_cvt_pk_bf16_f32 v105, v190, v191
	v_cvt_pk_bf16_f32 v106, v192, v193
	v_cvt_pk_bf16_f32 v107, v194, v195
	ds_write_b128 v101, v[104:107] offset:48

; template <int DH, int MODE>
; __device__ void attn_item(const Params& p, int layer, int b, int blk, int head, char* smem) {
;     ...
;     V_SCATTER_(vr0, 0);
;     V_SCATTER_(vr1, 1);
;     if (KCH > 2) {
;       V_SCATTER_(vr2, 2);
;       V_SCATTER_(vr3, 3);
;     }
;     KV_LOAD_(it + 1);
;     if (!wskip) {
;       float4* s4 = reinterpret_cast<float4*>(Sf + row * SSTR + half * 32);
;       char* prow = Pb + half * 8192 + row * 64;
;       if (MODE == 0) {
;         const int kjb = kj0 + half * 32;
;         float tmax = -1e30f;
; #pragma unroll
;         for (int c = 0; c < 8; ++c) {
;           float4 v = s4[c];
;           float e[4] = {v.x, v.y, v.z, v.w};
; #pragma unroll
;           for (int k = 0; k < 4; ++k) {
;             int kj = kjb + c * 4 + k;
;             bool valid = (kj > row) && (kj <= row + 128);
;             tmax = valid ? fmaxf(tmax, e[k]) : tmax;
;           }
;         }
;         tmax = fmaxf(tmax, __shfl_xor(tmax, 1));
;         float m_new = fmaxf(m_run, tmax);
;         float alpha = __builtin_amdgcn_exp2f(m_run - m_new);
.LBB0_487:
	s_or_b64 exec, exec, s[14:15]
	s_add_i32 s89, s89, 1
	s_min_i32 s14, s89, s87
	s_add_i32 s14, s14, s86
	s_lshl_b32 s14, s14, 6
	s_add_i32 s14, s14, s88
	s_ashr_i32 s15, s14, 31
	s_add_u32 s14, s14, s84
	s_addc_u32 s15, s15, 0
	s_waitcnt lgkmcnt(0)
	s_barrier
	ds_write_b16 v96, v48
	ds_write_b16_d16_hi v96, v48 offset:64
	ds_write_b16 v96, v49 offset:128
	ds_write_b16_d16_hi v96, v49 offset:192
	ds_write_b16 v96, v50 offset:256
	ds_write_b16_d16_hi v96, v50 offset:320
	ds_write_b16 v96, v51 offset:384
	ds_write_b16_d16_hi v96, v51 offset:448
	s_waitcnt vmcnt(0)
	ds_write_b16 v96, v52 offset:2048
	ds_write_b16_d16_hi v96, v52 offset:2112
	ds_write_b16 v96, v53 offset:2176
	ds_write_b16_d16_hi v96, v53 offset:2240
	ds_write_b16 v96, v54 offset:2304
	ds_write_b16_d16_hi v96, v54 offset:2368
	ds_write_b16 v96, v55 offset:2432
	ds_write_b16_d16_hi v96, v55 offset:2496
	v_lshl_add_u64 v[48:49], s[14:15], 0, v[66:67]
	v_mad_u64_u32 v[52:53], s[20:21], v48, s63, v[76:77]
	v_or_b32_e32 v48, s14, v72
	v_mad_i32_i24 v53, v49, s63, v53
	v_mad_u64_u32 v[54:55], s[20:21], v48, s63, v[78:79]
	v_add_co_u32_e32 v48, vcc, 0x4c000, v52
	v_mad_i32_i24 v55, s15, v160, v55
	s_nop 0
	v_addc_co_u32_e32 v49, vcc, 0, v53, vcc
	global_load_dwordx4 v[60:63], v[48:49], off
	s_nop 0
	global_load_dwordx4 v[48:51], v[54:55], off
	global_load_dwordx4 v[56:59], v[52:53], off
	s_nop 0
	global_load_dwordx4 v[52:55], v[54:55], off offset:64
	s_and_saveexec_b64 s[54:55], s[52:53]
	s_cbranch_execz .LBB0_509
	v_or_b32_e32 v101, s16, v89
	s_movk_i32 s91, 0x80
	ds_read_b128 v[164:167], v90 offset:16384
	ds_read_b128 v[168:171], v90 offset:16400
	ds_read_b128 v[172:175], v90 offset:16416
	ds_read_b128 v[176:179], v90 offset:16432
	ds_read_b128 v[180:183], v90 offset:16448
	ds_read_b128 v[184:187], v90 offset:16464
	ds_read_b128 v[188:191], v90 offset:16480
	ds_read_b128 v[192:195], v90 offset:16496
	v_sub_u32_e32 v102, v80, v101
	v_mov_b32_e32 v83, 0xf149f2ca
	v_add_u32_e32 v103, -31, v102
	v_cmp_gt_u32_e32 vcc, 0x61, v103
	s_cmp_eq_u64 vcc, exec
	s_cbranch_scc1 .Lswa_tfast_2
	v_mov_b32_e32 v161, v102
	v_add_u32_e32 v162, -1, v102
	v_add_u32_e32 v163, -2, v102
	v_cmp_gt_u32_e32 vcc, s91, v161
	v_cmp_gt_u32_e64 s[92:93], s91, v162
	v_cmp_gt_u32_e64 s[94:95], s91, v163
	s_waitcnt lgkmcnt(7)
	v_cndmask_b32_e32 v200, v83, v164, vcc
	v_cndmask_b32_e64 v201, v83, v165, s[92:93]
	v_cndmask_b32_e64 v202, v83, v166, s[94:95]
	v_add_u32_e32 v161, -3, v102
	v_add_u32_e32 v162, -4, v102
	v_add_u32_e32 v163, -5, v102
	v_cmp_gt_u32_e32 vcc, s91, v161
	v_cmp_gt_u32_e64 s[92:93], s91, v162
	v_cmp_gt_u32_e64 s[94:95], s91, v163
	s_waitcnt lgkmcnt(6)
	v_cndmask_b32_e32 v203, v83, v167, vcc
	v_cndmask_b32_e64 v204, v83, v168, s[92:93]
	v_cndmask_b32_e64 v205, v83, v169, s[94:95]
	v_add_u32_e32 v161, -6, v102
	v_add_u32_e32 v162, -7, v102
	v_add_u32_e32 v163, -8, v102
	v_cmp_gt_u32_e32 vcc, s91, v161
	v_cmp_gt_u32_e64 s[92:93], s91, v162
	v_cmp_gt_u32_e64 s[94:95], s91, v163
	s_waitcnt lgkmcnt(5)
	v_cndmask_b32_e32 v206, v83, v170, vcc
	v_cndmask_b32_e64 v207, v83, v171, s[92:93]
	v_cndmask_b32_e64 v208, v83, v172, s[94:95]
	v_add_u32_e32 v161, -9, v102
	v_add_u32_e32 v162, -10, v102
	v_add_u32_e32 v163, -11, v102
	v_cmp_gt_u32_e32 vcc, s91, v161
	v_cmp_gt_u32_e64 s[92:93], s91, v162
	v_cmp_gt_u32_e64 s[94:95], s91, v163
	v_cndmask_b32_e32 v209, v83, v173, vcc
	v_cndmask_b32_e64 v210, v83, v174, s[92:93]
	v_cndmask_b32_e64 v211, v83, v175, s[94:95]
	v_add_u32_e32 v161, -12, v102
	v_add_u32_e32 v162, -13, v102
	v_add_u32_e32 v163, -14, v102
	v_cmp_gt_u32_e32 vcc, s91, v161
	v_cmp_gt_u32_e64 s[92:93], s91, v162
	v_cmp_gt_u32_e64 s[94:95], s91, v163
	s_waitcnt lgkmcnt(4)
	v_cndmask_b32_e32 v212, v83, v176, vcc
	v_cndmask_b32_e64 v213, v83, v177, s[92:93]
	v_cndmask_b32_e64 v214, v83, v178, s[94:95]
	v_add_u32_e32 v161, -15, v102
	v_add_u32_e32 v162, -16, v102
	v_add_u32_e32 v163, 0xffffffef, v102
	v_cmp_gt_u32_e32 vcc, s91, v161
	v_cmp_gt_u32_e64 s[92:93], s91, v162
	v_cmp_gt_u32_e64 s[94:95], s91, v163
	s_waitcnt lgkmcnt(3)
	v_cndmask_b32_e32 v215, v83, v179, vcc
	v_cndmask_b32_e64 v216, v83, v180, s[92:93]
	v_cndmask_b32_e64 v217, v83, v181, s[94:95]
	v_add_u32_e32 v161, 0xffffffee, v102
	v_add_u32_e32 v162, 0xffffffed, v102
	v_add_u32_e32 v163, 0xffffffec, v102
	v_cmp_gt_u32_e32 vcc, s91, v161
	v_cmp_gt_u32_e64 s[92:93], s91, v162
	v_cmp_gt_u32_e64 s[94:95], s91, v163
	s_waitcnt lgkmcnt(2)
	v_cndmask_b32_e32 v218, v83, v182, vcc
	v_cndmask_b32_e64 v219, v83, v183, s[92:93]
	v_cndmask_b32_e64 v220, v83, v184, s[94:95]
	v_add_u32_e32 v161, 0xffffffeb, v102
	v_add_u32_e32 v162, 0xffffffea, v102
	v_add_u32_e32 v163, 0xffffffe9, v102
	v_cmp_gt_u32_e32 vcc, s91, v161
	v_cmp_gt_u32_e64 s[92:93], s91, v162
	v_cmp_gt_u32_e64 s[94:95], s91, v163
	v_cndmask_b32_e32 v221, v83, v185, vcc
	v_cndmask_b32_e64 v222, v83, v186, s[92:93]
	v_cndmask_b32_e64 v223, v83, v187, s[94:95]
	v_add_u32_e32 v161, 0xffffffe8, v102
	v_add_u32_e32 v162, 0xffffffe7, v102
	v_add_u32_e32 v163, 0xffffffe6, v102
	v_cmp_gt_u32_e32 vcc, s91, v161
	v_cmp_gt_u32_e64 s[92:93], s91, v162
	v_cmp_gt_u32_e64 s[94:95], s91, v163
	s_waitcnt lgkmcnt(1)
	v_cndmask_b32_e32 v224, v83, v188, vcc
	v_cndmask_b32_e64 v225, v83, v189, s[92:93]
	v_cndmask_b32_e64 v226, v83, v190, s[94:95]
	v_add_u32_e32 v161, 0xffffffe5, v102
	v_add_u32_e32 v162, 0xffffffe4, v102
	v_add_u32_e32 v163, 0xffffffe3, v102
	v_cmp_gt_u32_e32 vcc, s91, v161
	v_cmp_gt_u32_e64 s[92:93], s91, v162
	v_cmp_gt_u32_e64 s[94:95], s91, v163
	s_waitcnt lgkmcnt(0)
	v_cndmask_b32_e32 v227, v83, v191, vcc
	v_cndmask_b32_e64 v228, v83, v192, s[92:93]
	v_cndmask_b32_e64 v229, v83, v193, s[94:95]
	v_add_u32_e32 v161, 0xffffffe2, v102
	v_add_u32_e32 v162, 0xffffffe1, v102
	v_cmp_gt_u32_e32 vcc, s91, v161
	v_cmp_gt_u32_e64 s[92:93], s91, v162
	s_nop 0
	v_cndmask_b32_e32 v230, v83, v194, vcc
	v_cndmask_b32_e64 v231, v83, v195, s[92:93]
	v_max3_f32 v200, v200, v201, v202
	v_max3_f32 v203, v203, v204, v205
	v_max3_f32 v206, v206, v207, v208
	v_max3_f32 v209, v209, v210, v211
	v_max3_f32 v212, v212, v213, v214
	v_max3_f32 v215, v215, v216, v217
	v_max3_f32 v218, v218, v219, v220
	v_max3_f32 v221, v221, v222, v223
	v_max3_f32 v224, v224, v225, v226
	v_max3_f32 v227, v227, v228, v229
	v_max_f32_e32 v230, v230, v231
	v_max3_f32 v200, v200, v203, v206
	v_max3_f32 v209, v209, v212, v215
	v_max3_f32 v218, v218, v221, v224
	v_max_f32_e32 v227, v227, v230
	v_max3_f32 v200, v200, v209, v218
	v_max_f32_e32 v200, v200, v227
	v_mov_b32_e32 v82, v200
	s_branch .Lswa_tdone_2

; template <int DH, int MODE>
; __device__ void attn_item(const Params& p, int layer, int b, int blk, int head, char* smem) {
;     ...
;         tmax = fmaxf(tmax, __shfl_xor(tmax, 1));
;         float m_new = fmaxf(m_run, tmax);
;         float alpha = __builtin_amdgcn_exp2f(m_run - m_new);
;         float psum = 0.f;
; #pragma unroll 2
;         for (int s8 = 0; s8 < 4; ++s8) {
;           float4 va = s4[2 * s8], vb = s4[2 * s8 + 1];
;           float e[8] = {va.x, va.y, va.z, va.w, vb.x, vb.y, vb.z, vb.w};
;           float pv[8];
; #pragma unroll
;           for (int k = 0; k < 8; ++k) {
;             int kj = kjb + s8 * 8 + k;
;             bool valid = (kj > row) && (kj <= row + 128);
;             float pe = valid ? __builtin_amdgcn_exp2f(e[k] - m_new) : 0.f;
;             pv[k] = pe;
;             psum += pe;
;           }
.Lswa_tdone_2:
	v_cmp_lt_i32_e32 vcc, v157, v158
	s_mov_b32 s90, 0
	v_mov_b32_e32 v103, 0
	v_cndmask_b32_e32 v83, v156, v157, vcc
	v_lshlrev_b32_e32 v83, 2, v83
	ds_bpermute_b32 v101, v83, v82
	v_mov_b32_e32 v102, v91
	s_waitcnt lgkmcnt(0)
	v_max3_f32 v82, v87, v82, v101
	v_mov_b32_e32 v101, v93
	s_movk_i32 s91, 0x80
	v_sub_u32_e32 v112, v80, v92
	v_add_u32_e32 v113, -31, v112
	v_cmp_gt_u32_e32 vcc, 0x61, v113
	s_cmp_eq_u64 vcc, exec
	s_cbranch_scc1 .Lswa_pfast_2
	v_sub_f32_e32 v164, v164, v82
	v_sub_f32_e32 v165, v165, v82
	v_sub_f32_e32 v166, v166, v82
	v_exp_f32_e32 v164, v164
	v_exp_f32_e32 v165, v165
	v_exp_f32_e32 v166, v166
	v_mov_b32_e32 v196, v112
	v_add_u32_e32 v197, -1, v112
	v_add_u32_e32 v198, -2, v112
	v_cmp_gt_u32_e32 vcc, s91, v196
	v_cmp_gt_u32_e64 s[92:93], s91, v197
	v_cmp_gt_u32_e64 s[94:95], s91, v198
	v_cndmask_b32_e32 v164, 0, v164, vcc
	v_cndmask_b32_e64 v165, 0, v165, s[92:93]
	v_cndmask_b32_e64 v166, 0, v166, s[94:95]
	v_add_f32_e32 v103, v103, v164
	v_add_f32_e32 v103, v103, v165
	v_add_f32_e32 v103, v103, v166
	v_sub_f32_e32 v167, v167, v82
	v_sub_f32_e32 v168, v168, v82
	v_sub_f32_e32 v169, v169, v82
	v_exp_f32_e32 v167, v167
	v_exp_f32_e32 v168, v168
	v_exp_f32_e32 v169, v169
	v_add_u32_e32 v196, -3, v112
	v_add_u32_e32 v197, -4, v112
	v_add_u32_e32 v198, -5, v112
	v_cmp_gt_u32_e32 vcc, s91, v196
	v_cmp_gt_u32_e64 s[92:93], s91, v197
	v_cmp_gt_u32_e64 s[94:95], s91, v198
	v_cndmask_b32_e32 v167, 0, v167, vcc
	v_cndmask_b32_e64 v168, 0, v168, s[92:93]
	v_cndmask_b32_e64 v169, 0, v169, s[94:95]
	v_add_f32_e32 v103, v103, v167
	v_add_f32_e32 v103, v103, v168
	v_add_f32_e32 v103, v103, v169
	v_sub_f32_e32 v170, v170, v82
	v_sub_f32_e32 v171, v171, v82
	v_sub_f32_e32 v172, v172, v82
	v_exp_f32_e32 v170, v170
	v_exp_f32_e32 v171, v171
	v_exp_f32_e32 v172, v172
	v_add_u32_e32 v196, -6, v112
	v_add_u32_e32 v197, -7, v112
	v_add_u32_e32 v198, -8, v112
	v_cmp_gt_u32_e32 vcc, s91, v196
	v_cmp_gt_u32_e64 s[92:93], s91, v197
	v_cmp_gt_u32_e64 s[94:95], s91, v198
	v_cndmask_b32_e32 v170, 0, v170, vcc
	v_cndmask_b32_e64 v171, 0, v171, s[92:93]
	v_cndmask_b32_e64 v172, 0, v172, s[94:95]
	v_add_f32_e32 v103, v103, v170
	v_add_f32_e32 v103, v103, v171
	v_add_f32_e32 v103, v103, v172
	v_sub_f32_e32 v173, v173, v82
	v_sub_f32_e32 v174, v174, v82
	v_sub_f32_e32 v175, v175, v82
	v_exp_f32_e32 v173, v173
	v_exp_f32_e32 v174, v174
	v_exp_f32_e32 v175, v175
	v_add_u32_e32 v196, -9, v112
	v_add_u32_e32 v197, -10, v112
	v_add_u32_e32 v198, -11, v112
	v_cmp_gt_u32_e32 vcc, s91, v196
	v_cmp_gt_u32_e64 s[92:93], s91, v197
	v_cmp_gt_u32_e64 s[94:95], s91, v198
	v_cndmask_b32_e32 v173, 0, v173, vcc
	v_cndmask_b32_e64 v174, 0, v174, s[92:93]
	v_cndmask_b32_e64 v175, 0, v175, s[94:95]
	v_add_f32_e32 v103, v103, v173
	v_add_f32_e32 v103, v103, v174
	v_add_f32_e32 v103, v103, v175
	v_sub_f32_e32 v176, v176, v82
	v_sub_f32_e32 v177, v177, v82
	v_sub_f32_e32 v178, v178, v82
	v_exp_f32_e32 v176, v176
	v_exp_f32_e32 v177, v177
	v_exp_f32_e32 v178, v178
	v_add_u32_e32 v196, -12, v112
	v_add_u32_e32 v197, -13, v112
	v_add_u32_e32 v198, -14, v112
	v_cmp_gt_u32_e32 vcc, s91, v196
	v_cmp_gt_u32_e64 s[92:93], s91, v197
	v_cmp_gt_u32_e64 s[94:95], s91, v198
	v_cndmask_b32_e32 v176, 0, v176, vcc
	v_cndmask_b32_e64 v177, 0, v177, s[92:93]
	v_cndmask_b32_e64 v178, 0, v178, s[94:95]
	v_add_f32_e32 v103, v103, v176
	v_add_f32_e32 v103, v103, v177
	v_add_f32_e32 v103, v103, v178
	v_sub_f32_e32 v179, v179, v82
	v_sub_f32_e32 v180, v180, v82
	v_sub_f32_e32 v181, v181, v82
	v_exp_f32_e32 v179, v179
	v_exp_f32_e32 v180, v180
	v_exp_f32_e32 v181, v181
	v_add_u32_e32 v196, -15, v112
	v_add_u32_e32 v197, -16, v112
	v_add_u32_e32 v198, 0xffffffef, v112
	v_cmp_gt_u32_e32 vcc, s91, v196
	v_cmp_gt_u32_e64 s[92:93], s91, v197
	v_cmp_gt_u32_e64 s[94:95], s91, v198
	v_cndmask_b32_e32 v179, 0, v179, vcc
; __device__ __forceinline__ unsigned pack2(float a, float b) { return (unsigned)f2bf(a) | ((unsigned)f2bf(b) << 16); }
; template <int DH, int MODE>
; __device__ void attn_item(const Params& p, int layer, int b, int blk, int head, char* smem) {
;     ...
; #pragma unroll 2
;         for (int s8 = 0; s8 < 4; ++s8) {
;           float4 va = s4[2 * s8], vb = s4[2 * s8 + 1];
;           float e[8] = {va.x, va.y, va.z, va.w, vb.x, vb.y, vb.z, vb.w};
;           float pv[8];
; #pragma unroll
;           for (int k = 0; k < 8; ++k) {
;             int kj = kjb + s8 * 8 + k;
;             bool valid = (kj > row) && (kj <= row + 128);
;             float pe = valid ? __builtin_amdgcn_exp2f(e[k] - m_new) : 0.f;
;             pv[k] = pe;
;             psum += pe;
;           }
;           uint4 ov;
;           ov.x = pack2(pv[0], pv[1]); ov.y = pack2(pv[2], pv[3]);
;           ov.z = pack2(pv[4], pv[5]); ov.w = pack2(pv[6], pv[7]);
;           *reinterpret_cast<uint4*>(prow + s8 * 16) = ov;
;         }
	v_cndmask_b32_e64 v180, 0, v180, s[92:93]
	v_cndmask_b32_e64 v181, 0, v181, s[94:95]
	v_add_f32_e32 v103, v103, v179
	v_add_f32_e32 v103, v103, v180
	v_add_f32_e32 v103, v103, v181
	v_sub_f32_e32 v182, v182, v82
	v_sub_f32_e32 v183, v183, v82
	v_sub_f32_e32 v184, v184, v82
	v_exp_f32_e32 v182, v182
	v_exp_f32_e32 v183, v183
	v_exp_f32_e32 v184, v184
	v_add_u32_e32 v196, 0xffffffee, v112
	v_add_u32_e32 v197, 0xffffffed, v112
	v_add_u32_e32 v198, 0xffffffec, v112
	v_cmp_gt_u32_e32 vcc, s91, v196
	v_cmp_gt_u32_e64 s[92:93], s91, v197
	v_cmp_gt_u32_e64 s[94:95], s91, v198
	v_cndmask_b32_e32 v182, 0, v182, vcc
	v_cndmask_b32_e64 v183, 0, v183, s[92:93]
	v_cndmask_b32_e64 v184, 0, v184, s[94:95]
	v_add_f32_e32 v103, v103, v182
	v_add_f32_e32 v103, v103, v183
	v_add_f32_e32 v103, v103, v184
	v_sub_f32_e32 v185, v185, v82
	v_sub_f32_e32 v186, v186, v82
	v_sub_f32_e32 v187, v187, v82
	v_exp_f32_e32 v185, v185
	v_exp_f32_e32 v186, v186
	v_exp_f32_e32 v187, v187
	v_add_u32_e32 v196, 0xffffffeb, v112
	v_add_u32_e32 v197, 0xffffffea, v112
	v_add_u32_e32 v198, 0xffffffe9, v112
	v_cmp_gt_u32_e32 vcc, s91, v196
	v_cmp_gt_u32_e64 s[92:93], s91, v197
	v_cmp_gt_u32_e64 s[94:95], s91, v198
	v_cndmask_b32_e32 v185, 0, v185, vcc
	v_cndmask_b32_e64 v186, 0, v186, s[92:93]
	v_cndmask_b32_e64 v187, 0, v187, s[94:95]
	v_add_f32_e32 v103, v103, v185
	v_add_f32_e32 v103, v103, v186
	v_add_f32_e32 v103, v103, v187
	v_sub_f32_e32 v188, v188, v82
	v_sub_f32_e32 v189, v189, v82
	v_sub_f32_e32 v190, v190, v82
	v_exp_f32_e32 v188, v188
	v_exp_f32_e32 v189, v189
	v_exp_f32_e32 v190, v190
	v_add_u32_e32 v196, 0xffffffe8, v112
	v_add_u32_e32 v197, 0xffffffe7, v112
	v_add_u32_e32 v198, 0xffffffe6, v112
	v_cmp_gt_u32_e32 vcc, s91, v196
	v_cmp_gt_u32_e64 s[92:93], s91, v197
	v_cmp_gt_u32_e64 s[94:95], s91, v198
	v_cndmask_b32_e32 v188, 0, v188, vcc
	v_cndmask_b32_e64 v189, 0, v189, s[92:93]
	v_cndmask_b32_e64 v190, 0, v190, s[94:95]
	v_add_f32_e32 v103, v103, v188
	v_add_f32_e32 v103, v103, v189
	v_add_f32_e32 v103, v103, v190
	v_sub_f32_e32 v191, v191, v82
	v_sub_f32_e32 v192, v192, v82
	v_sub_f32_e32 v193, v193, v82
	v_exp_f32_e32 v191, v191
	v_exp_f32_e32 v192, v192
	v_exp_f32_e32 v193, v193
	v_add_u32_e32 v196, 0xffffffe5, v112
	v_add_u32_e32 v197, 0xffffffe4, v112
	v_add_u32_e32 v198, 0xffffffe3, v112
	v_cmp_gt_u32_e32 vcc, s91, v196
	v_cmp_gt_u32_e64 s[92:93], s91, v197
	v_cmp_gt_u32_e64 s[94:95], s91, v198
	v_cndmask_b32_e32 v191, 0, v191, vcc
	v_cndmask_b32_e64 v192, 0, v192, s[92:93]
	v_cndmask_b32_e64 v193, 0, v193, s[94:95]
	v_add_f32_e32 v103, v103, v191
	v_add_f32_e32 v103, v103, v192
	v_add_f32_e32 v103, v103, v193
	v_sub_f32_e32 v194, v194, v82
	v_sub_f32_e32 v195, v195, v82
	v_exp_f32_e32 v194, v194
	v_exp_f32_e32 v195, v195
	v_add_u32_e32 v196, 0xffffffe2, v112
	v_add_u32_e32 v197, 0xffffffe1, v112
	v_cmp_gt_u32_e32 vcc, s91, v196
	v_cmp_gt_u32_e64 s[92:93], s91, v197
	s_nop 0
	v_cndmask_b32_e32 v194, 0, v194, vcc
	v_cndmask_b32_e64 v195, 0, v195, s[92:93]
	v_add_f32_e32 v103, v103, v194
	v_add_f32_e32 v103, v103, v195
	v_cvt_pk_bf16_f32 v104, v164, v165
	v_cvt_pk_bf16_f32 v105, v166, v167
	v_cvt_pk_bf16_f32 v106, v168, v169
	v_cvt_pk_bf16_f32 v107, v170, v171
	ds_write_b128 v101, v[104:107]
	s_nop 0
	v_cvt_pk_bf16_f32 v104, v172, v173
	v_cvt_pk_bf16_f32 v105, v174, v175
	v_cvt_pk_bf16_f32 v106, v176, v177
	v_cvt_pk_bf16_f32 v107, v178, v179
	ds_write_b128 v101, v[104:107] offset:16
	s_nop 0
	v_cvt_pk_bf16_f32 v104, v180, v181
	v_cvt_pk_bf16_f32 v105, v182, v183
	v_cvt_pk_bf16_f32 v106, v184, v185
	v_cvt_pk_bf16_f32 v107, v186, v187
	ds_write_b128 v101, v[104:107] offset:32
	s_nop 0
	v_cvt_pk_bf16_f32 v104, v188, v189
	v_cvt_pk_bf16_f32 v105, v190, v191
	v_cvt_pk_bf16_f32 v106, v192, v193
	v_cvt_pk_bf16_f32 v107, v194, v195
	ds_write_b128 v101, v[104:107] offset:48
	s_branch .Lswa_pdone_2

; template <int DH, int MODE>
; __device__ void attn_item(const Params& p, int layer, int b, int blk, int head, char* smem) {
;     ...
;     V_SCATTER_(vr0, 0);
;     V_SCATTER_(vr1, 1);
;     if (KCH > 2) {
;       V_SCATTER_(vr2, 2);
;       V_SCATTER_(vr3, 3);
;     }
;     KV_LOAD_(it + 1);
;     if (!wskip) {
;       float4* s4 = reinterpret_cast<float4*>(Sf + row * SSTR + half * 32);
;       char* prow = Pb + half * 8192 + row * 64;
;       if (MODE == 0) {
;         const int kjb = kj0 + half * 32;
;         float tmax = -1e30f;
; #pragma unroll
;         for (int c = 0; c < 8; ++c) {
;           float4 v = s4[c];
;           float e[4] = {v.x, v.y, v.z, v.w};
; #pragma unroll
;           for (int k = 0; k < 4; ++k) {
;             int kj = kjb + c * 4 + k;
;             bool valid = (kj > row) && (kj <= row + 128);
;             tmax = valid ? fmaxf(tmax, e[k]) : tmax;
;           }
;         }
;         tmax = fmaxf(tmax, __shfl_xor(tmax, 1));
;         float m_new = fmaxf(m_run, tmax);
;         float alpha = __builtin_amdgcn_exp2f(m_run - m_new);
.LBB0_808:
	s_or_b64 exec, exec, s[14:15]
	s_add_i32 s89, s89, 1
	s_min_i32 s14, s89, s87
	s_add_i32 s14, s14, s86
	s_lshl_b32 s14, s14, 6
	s_add_i32 s14, s14, s88
	s_ashr_i32 s15, s14, 31
	s_add_u32 s14, s14, s84
	s_addc_u32 s15, s15, 0
	s_waitcnt lgkmcnt(0)
	s_barrier
	ds_write_b16 v96, v48
	ds_write_b16_d16_hi v96, v48 offset:64
	ds_write_b16 v96, v49 offset:128
	ds_write_b16_d16_hi v96, v49 offset:192
	ds_write_b16 v96, v50 offset:256
	ds_write_b16_d16_hi v96, v50 offset:320
	ds_write_b16 v96, v51 offset:384
	ds_write_b16_d16_hi v96, v51 offset:448
	s_waitcnt vmcnt(0)
	ds_write_b16 v96, v52 offset:2048
	ds_write_b16_d16_hi v96, v52 offset:2112
	ds_write_b16 v96, v53 offset:2176
	ds_write_b16_d16_hi v96, v53 offset:2240
	ds_write_b16 v96, v54 offset:2304
	ds_write_b16_d16_hi v96, v54 offset:2368
	ds_write_b16 v96, v55 offset:2432
	ds_write_b16_d16_hi v96, v55 offset:2496
	v_lshl_add_u64 v[48:49], s[14:15], 0, v[66:67]
	v_mad_u64_u32 v[52:53], s[20:21], v48, s45, v[76:77]
	v_or_b32_e32 v48, s14, v72
	v_mad_i32_i24 v53, v49, s45, v53
	v_mad_u64_u32 v[54:55], s[20:21], v48, s45, v[78:79]
	v_add_co_u32_e32 v48, vcc, 0x4c000, v52
	v_mad_i32_i24 v55, s15, v160, v55
	s_nop 0
	v_addc_co_u32_e32 v49, vcc, 0, v53, vcc
	global_load_dwordx4 v[60:63], v[48:49], off
	s_nop 0
	global_load_dwordx4 v[48:51], v[54:55], off
	global_load_dwordx4 v[56:59], v[52:53], off
	s_nop 0
	global_load_dwordx4 v[52:55], v[54:55], off offset:64
	s_and_saveexec_b64 s[52:53], s[50:51]
	s_cbranch_execz .LBB0_830
	v_or_b32_e32 v101, s16, v89
	s_movk_i32 s91, 0x80
	ds_read_b128 v[164:167], v90 offset:16384
	ds_read_b128 v[168:171], v90 offset:16400
	ds_read_b128 v[172:175], v90 offset:16416
	ds_read_b128 v[176:179], v90 offset:16432
	ds_read_b128 v[180:183], v90 offset:16448
	ds_read_b128 v[184:187], v90 offset:16464
	ds_read_b128 v[188:191], v90 offset:16480
	ds_read_b128 v[192:195], v90 offset:16496
	v_sub_u32_e32 v102, v80, v101
	v_mov_b32_e32 v83, 0xf149f2ca
	v_add_u32_e32 v103, -31, v102
	v_cmp_gt_u32_e32 vcc, 0x61, v103
	s_cmp_eq_u64 vcc, exec
	s_cbranch_scc1 .Lswa_tfast_1
	v_mov_b32_e32 v161, v102
	v_add_u32_e32 v162, -1, v102
	v_add_u32_e32 v163, -2, v102
	v_cmp_gt_u32_e32 vcc, s91, v161
	v_cmp_gt_u32_e64 s[92:93], s91, v162
	v_cmp_gt_u32_e64 s[94:95], s91, v163
	s_waitcnt lgkmcnt(7)
	v_cndmask_b32_e32 v200, v83, v164, vcc
	v_cndmask_b32_e64 v201, v83, v165, s[92:93]
	v_cndmask_b32_e64 v202, v83, v166, s[94:95]
	v_add_u32_e32 v161, -3, v102
	v_add_u32_e32 v162, -4, v102
	v_add_u32_e32 v163, -5, v102
	v_cmp_gt_u32_e32 vcc, s91, v161
	v_cmp_gt_u32_e64 s[92:93], s91, v162
	v_cmp_gt_u32_e64 s[94:95], s91, v163
	s_waitcnt lgkmcnt(6)
	v_cndmask_b32_e32 v203, v83, v167, vcc
	v_cndmask_b32_e64 v204, v83, v168, s[92:93]
	v_cndmask_b32_e64 v205, v83, v169, s[94:95]
	v_add_u32_e32 v161, -6, v102
	v_add_u32_e32 v162, -7, v102
	v_add_u32_e32 v163, -8, v102
	v_cmp_gt_u32_e32 vcc, s91, v161
	v_cmp_gt_u32_e64 s[92:93], s91, v162
	v_cmp_gt_u32_e64 s[94:95], s91, v163
	s_waitcnt lgkmcnt(5)
	v_cndmask_b32_e32 v206, v83, v170, vcc
	v_cndmask_b32_e64 v207, v83, v171, s[92:93]
	v_cndmask_b32_e64 v208, v83, v172, s[94:95]
	v_add_u32_e32 v161, -9, v102
	v_add_u32_e32 v162, -10, v102
	v_add_u32_e32 v163, -11, v102
	v_cmp_gt_u32_e32 vcc, s91, v161
	v_cmp_gt_u32_e64 s[92:93], s91, v162
	v_cmp_gt_u32_e64 s[94:95], s91, v163
	v_cndmask_b32_e32 v209, v83, v173, vcc
	v_cndmask_b32_e64 v210, v83, v174, s[92:93]
	v_cndmask_b32_e64 v211, v83, v175, s[94:95]
	v_add_u32_e32 v161, -12, v102
	v_add_u32_e32 v162, -13, v102
	v_add_u32_e32 v163, -14, v102
	v_cmp_gt_u32_e32 vcc, s91, v161
	v_cmp_gt_u32_e64 s[92:93], s91, v162
	v_cmp_gt_u32_e64 s[94:95], s91, v163
	s_waitcnt lgkmcnt(4)
	v_cndmask_b32_e32 v212, v83, v176, vcc
	v_cndmask_b32_e64 v213, v83, v177, s[92:93]
	v_cndmask_b32_e64 v214, v83, v178, s[94:95]
	v_add_u32_e32 v161, -15, v102
	v_add_u32_e32 v162, -16, v102
	v_add_u32_e32 v163, 0xffffffef, v102
	v_cmp_gt_u32_e32 vcc, s91, v161
	v_cmp_gt_u32_e64 s[92:93], s91, v162
	v_cmp_gt_u32_e64 s[94:95], s91, v163
	s_waitcnt lgkmcnt(3)
	v_cndmask_b32_e32 v215, v83, v179, vcc
	v_cndmask_b32_e64 v216, v83, v180, s[92:93]
	v_cndmask_b32_e64 v217, v83, v181, s[94:95]
	v_add_u32_e32 v161, 0xffffffee, v102
	v_add_u32_e32 v162, 0xffffffed, v102
	v_add_u32_e32 v163, 0xffffffec, v102
	v_cmp_gt_u32_e32 vcc, s91, v161
	v_cmp_gt_u32_e64 s[92:93], s91, v162
	v_cmp_gt_u32_e64 s[94:95], s91, v163
	s_waitcnt lgkmcnt(2)
	v_cndmask_b32_e32 v218, v83, v182, vcc
	v_cndmask_b32_e64 v219, v83, v183, s[92:93]
	v_cndmask_b32_e64 v220, v83, v184, s[94:95]
	v_add_u32_e32 v161, 0xffffffeb, v102
	v_add_u32_e32 v162, 0xffffffea, v102
	v_add_u32_e32 v163, 0xffffffe9, v102
	v_cmp_gt_u32_e32 vcc, s91, v161
	v_cmp_gt_u32_e64 s[92:93], s91, v162
	v_cmp_gt_u32_e64 s[94:95], s91, v163
	v_cndmask_b32_e32 v221, v83, v185, vcc
	v_cndmask_b32_e64 v222, v83, v186, s[92:93]
	v_cndmask_b32_e64 v223, v83, v187, s[94:95]
	v_add_u32_e32 v161, 0xffffffe8, v102
	v_add_u32_e32 v162, 0xffffffe7, v102
	v_add_u32_e32 v163, 0xffffffe6, v102
	v_cmp_gt_u32_e32 vcc, s91, v161
	v_cmp_gt_u32_e64 s[92:93], s91, v162
	v_cmp_gt_u32_e64 s[94:95], s91, v163
	s_waitcnt lgkmcnt(1)
	v_cndmask_b32_e32 v224, v83, v188, vcc
	v_cndmask_b32_e64 v225, v83, v189, s[92:93]
	v_cndmask_b32_e64 v226, v83, v190, s[94:95]
	v_add_u32_e32 v161, 0xffffffe5, v102
	v_add_u32_e32 v162, 0xffffffe4, v102
	v_add_u32_e32 v163, 0xffffffe3, v102
	v_cmp_gt_u32_e32 vcc, s91, v161
	v_cmp_gt_u32_e64 s[92:93], s91, v162
	v_cmp_gt_u32_e64 s[94:95], s91, v163
	s_waitcnt lgkmcnt(0)
	v_cndmask_b32_e32 v227, v83, v191, vcc
	v_cndmask_b32_e64 v228, v83, v192, s[92:93]
	v_cndmask_b32_e64 v229, v83, v193, s[94:95]
	v_add_u32_e32 v161, 0xffffffe2, v102
	v_add_u32_e32 v162, 0xffffffe1, v102
	v_cmp_gt_u32_e32 vcc, s91, v161
	v_cmp_gt_u32_e64 s[92:93], s91, v162
	s_nop 0
	v_cndmask_b32_e32 v230, v83, v194, vcc
	v_cndmask_b32_e64 v231, v83, v195, s[92:93]
	v_max3_f32 v200, v200, v201, v202
	v_max3_f32 v203, v203, v204, v205
	v_max3_f32 v206, v206, v207, v208
	v_max3_f32 v209, v209, v210, v211
	v_max3_f32 v212, v212, v213, v214
	v_max3_f32 v215, v215, v216, v217
	v_max3_f32 v218, v218, v219, v220
	v_max3_f32 v221, v221, v222, v223
	v_max3_f32 v224, v224, v225, v226
	v_max3_f32 v227, v227, v228, v229
	v_max_f32_e32 v230, v230, v231
	v_max3_f32 v200, v200, v203, v206
	v_max3_f32 v209, v209, v212, v215
	v_max3_f32 v218, v218, v221, v224
	v_max_f32_e32 v227, v227, v230
	v_max3_f32 v200, v200, v209, v218
	v_max_f32_e32 v200, v200, v227
	v_mov_b32_e32 v82, v200
	s_branch .Lswa_tdone_1

; template <int DH, int MODE>
; __device__ void attn_item(const Params& p, int layer, int b, int blk, int head, char* smem) {
;     ...
;     V_SCATTER_(vr0, 0);
;     V_SCATTER_(vr1, 1);
;     if (KCH > 2) {
;       V_SCATTER_(vr2, 2);
;       V_SCATTER_(vr3, 3);
;     }
;     KV_LOAD_(it + 1);
;     if (!wskip) {
;       float4* s4 = reinterpret_cast<float4*>(Sf + row * SSTR + half * 32);
;       char* prow = Pb + half * 8192 + row * 64;
;       if (MODE == 0) {
;         const int kjb = kj0 + half * 32;
;         float tmax = -1e30f;
; #pragma unroll
;         for (int c = 0; c < 8; ++c) {
;           float4 v = s4[c];
;           float e[4] = {v.x, v.y, v.z, v.w};
; #pragma unroll
;           for (int k = 0; k < 4; ++k) {
;             int kj = kjb + c * 4 + k;
;             bool valid = (kj > row) && (kj <= row + 128);
;             tmax = valid ? fmaxf(tmax, e[k]) : tmax;
;           }
;         }
;         tmax = fmaxf(tmax, __shfl_xor(tmax, 1));
;         float m_new = fmaxf(m_run, tmax);
;         float alpha = __builtin_amdgcn_exp2f(m_run - m_new);
.LBB0_1129:
	s_or_b64 exec, exec, s[8:9]
	s_add_i32 s82, s82, 1
	s_min_i32 s8, s82, s80
	s_add_i32 s8, s8, s79
	s_lshl_b32 s8, s8, 6
	s_add_i32 s8, s8, s81
	s_ashr_i32 s9, s8, 31
	s_add_u32 s8, s8, s77
	s_addc_u32 s9, s9, 0
	s_waitcnt lgkmcnt(0)
	s_barrier
	ds_write_b16 v96, v48
	ds_write_b16_d16_hi v96, v48 offset:64
	ds_write_b16 v96, v49 offset:128
	ds_write_b16_d16_hi v96, v49 offset:192
	ds_write_b16 v96, v50 offset:256
	ds_write_b16_d16_hi v96, v50 offset:320
	ds_write_b16 v96, v51 offset:384
	ds_write_b16_d16_hi v96, v51 offset:448
	s_waitcnt vmcnt(0)
	ds_write_b16 v96, v52 offset:2048
	ds_write_b16_d16_hi v96, v52 offset:2112
	ds_write_b16 v96, v53 offset:2176
	ds_write_b16_d16_hi v96, v53 offset:2240
	ds_write_b16 v96, v54 offset:2304
	ds_write_b16_d16_hi v96, v54 offset:2368
	ds_write_b16 v96, v55 offset:2432
	ds_write_b16_d16_hi v96, v55 offset:2496
	v_lshl_add_u64 v[48:49], s[8:9], 0, v[66:67]
	v_mad_u64_u32 v[52:53], s[12:13], v48, s39, v[76:77]
	v_or_b32_e32 v48, s8, v72
	v_mad_i32_i24 v53, v49, s39, v53
	v_mad_u64_u32 v[54:55], s[12:13], v48, s39, v[78:79]
	v_add_co_u32_e32 v48, vcc, 0x4c000, v52
	v_mad_i32_i24 v55, s9, v160, v55
	s_nop 0
	v_addc_co_u32_e32 v49, vcc, 0, v53, vcc
	global_load_dwordx4 v[60:63], v[48:49], off
	s_nop 0
	global_load_dwordx4 v[48:51], v[54:55], off
	global_load_dwordx4 v[56:59], v[52:53], off
	s_nop 0
	global_load_dwordx4 v[52:55], v[54:55], off offset:64
	s_and_saveexec_b64 s[46:47], s[44:45]
	s_cbranch_execz .LBB0_1151
	v_or_b32_e32 v101, s10, v89
	s_movk_i32 s91, 0x80
	ds_read_b128 v[164:167], v90 offset:16384
	ds_read_b128 v[168:171], v90 offset:16400
	ds_read_b128 v[172:175], v90 offset:16416
	ds_read_b128 v[176:179], v90 offset:16432
	ds_read_b128 v[180:183], v90 offset:16448
	ds_read_b128 v[184:187], v90 offset:16464
	ds_read_b128 v[188:191], v90 offset:16480
	ds_read_b128 v[192:195], v90 offset:16496
	v_sub_u32_e32 v102, v80, v101
	v_mov_b32_e32 v83, 0xf149f2ca
	v_add_u32_e32 v103, -31, v102
	v_cmp_gt_u32_e32 vcc, 0x61, v103
	s_cmp_eq_u64 vcc, exec
	s_cbranch_scc1 .Lswa_tfast_0
	v_mov_b32_e32 v161, v102
	v_add_u32_e32 v162, -1, v102
	v_add_u32_e32 v163, -2, v102
	v_cmp_gt_u32_e32 vcc, s91, v161
	v_cmp_gt_u32_e64 s[92:93], s91, v162
	v_cmp_gt_u32_e64 s[94:95], s91, v163
	s_waitcnt lgkmcnt(7)
	v_cndmask_b32_e32 v200, v83, v164, vcc
	v_cndmask_b32_e64 v201, v83, v165, s[92:93]
	v_cndmask_b32_e64 v202, v83, v166, s[94:95]
	v_add_u32_e32 v161, -3, v102
	v_add_u32_e32 v162, -4, v102
	v_add_u32_e32 v163, -5, v102
	v_cmp_gt_u32_e32 vcc, s91, v161
	v_cmp_gt_u32_e64 s[92:93], s91, v162
	v_cmp_gt_u32_e64 s[94:95], s91, v163
	s_waitcnt lgkmcnt(6)
	v_cndmask_b32_e32 v203, v83, v167, vcc
	v_cndmask_b32_e64 v204, v83, v168, s[92:93]
	v_cndmask_b32_e64 v205, v83, v169, s[94:95]
	v_add_u32_e32 v161, -6, v102
	v_add_u32_e32 v162, -7, v102
	v_add_u32_e32 v163, -8, v102
	v_cmp_gt_u32_e32 vcc, s91, v161
	v_cmp_gt_u32_e64 s[92:93], s91, v162
	v_cmp_gt_u32_e64 s[94:95], s91, v163
	s_waitcnt lgkmcnt(5)
	v_cndmask_b32_e32 v206, v83, v170, vcc
	v_cndmask_b32_e64 v207, v83, v171, s[92:93]
	v_cndmask_b32_e64 v208, v83, v172, s[94:95]
	v_add_u32_e32 v161, -9, v102
	v_add_u32_e32 v162, -10, v102
	v_add_u32_e32 v163, -11, v102
	v_cmp_gt_u32_e32 vcc, s91, v161
	v_cmp_gt_u32_e64 s[92:93], s91, v162
	v_cmp_gt_u32_e64 s[94:95], s91, v163
	v_cndmask_b32_e32 v209, v83, v173, vcc
	v_cndmask_b32_e64 v210, v83, v174, s[92:93]
	v_cndmask_b32_e64 v211, v83, v175, s[94:95]
	v_add_u32_e32 v161, -12, v102
	v_add_u32_e32 v162, -13, v102
	v_add_u32_e32 v163, -14, v102
	v_cmp_gt_u32_e32 vcc, s91, v161
	v_cmp_gt_u32_e64 s[92:93], s91, v162
	v_cmp_gt_u32_e64 s[94:95], s91, v163
	s_waitcnt lgkmcnt(4)
	v_cndmask_b32_e32 v212, v83, v176, vcc
	v_cndmask_b32_e64 v213, v83, v177, s[92:93]
	v_cndmask_b32_e64 v214, v83, v178, s[94:95]
	v_add_u32_e32 v161, -15, v102
	v_add_u32_e32 v162, -16, v102
	v_add_u32_e32 v163, 0xffffffef, v102
	v_cmp_gt_u32_e32 vcc, s91, v161
	v_cmp_gt_u32_e64 s[92:93], s91, v162
	v_cmp_gt_u32_e64 s[94:95], s91, v163
	s_waitcnt lgkmcnt(3)
	v_cndmask_b32_e32 v215, v83, v179, vcc
	v_cndmask_b32_e64 v216, v83, v180, s[92:93]
	v_cndmask_b32_e64 v217, v83, v181, s[94:95]
	v_add_u32_e32 v161, 0xffffffee, v102
	v_add_u32_e32 v162, 0xffffffed, v102
	v_add_u32_e32 v163, 0xffffffec, v102
	v_cmp_gt_u32_e32 vcc, s91, v161
	v_cmp_gt_u32_e64 s[92:93], s91, v162
	v_cmp_gt_u32_e64 s[94:95], s91, v163
	s_waitcnt lgkmcnt(2)
	v_cndmask_b32_e32 v218, v83, v182, vcc
	v_cndmask_b32_e64 v219, v83, v183, s[92:93]
	v_cndmask_b32_e64 v220, v83, v184, s[94:95]
	v_add_u32_e32 v161, 0xffffffeb, v102
	v_add_u32_e32 v162, 0xffffffea, v102
	v_add_u32_e32 v163, 0xffffffe9, v102
	v_cmp_gt_u32_e32 vcc, s91, v161
	v_cmp_gt_u32_e64 s[92:93], s91, v162
	v_cmp_gt_u32_e64 s[94:95], s91, v163
	v_cndmask_b32_e32 v221, v83, v185, vcc
	v_cndmask_b32_e64 v222, v83, v186, s[92:93]
	v_cndmask_b32_e64 v223, v83, v187, s[94:95]
	v_add_u32_e32 v161, 0xffffffe8, v102
	v_add_u32_e32 v162, 0xffffffe7, v102
	v_add_u32_e32 v163, 0xffffffe6, v102
	v_cmp_gt_u32_e32 vcc, s91, v161
	v_cmp_gt_u32_e64 s[92:93], s91, v162
	v_cmp_gt_u32_e64 s[94:95], s91, v163
	s_waitcnt lgkmcnt(1)
	v_cndmask_b32_e32 v224, v83, v188, vcc
	v_cndmask_b32_e64 v225, v83, v189, s[92:93]
	v_cndmask_b32_e64 v226, v83, v190, s[94:95]
	v_add_u32_e32 v161, 0xffffffe5, v102
	v_add_u32_e32 v162, 0xffffffe4, v102
	v_add_u32_e32 v163, 0xffffffe3, v102
	v_cmp_gt_u32_e32 vcc, s91, v161
	v_cmp_gt_u32_e64 s[92:93], s91, v162
	v_cmp_gt_u32_e64 s[94:95], s91, v163
	s_waitcnt lgkmcnt(0)
	v_cndmask_b32_e32 v227, v83, v191, vcc
	v_cndmask_b32_e64 v228, v83, v192, s[92:93]
	v_cndmask_b32_e64 v229, v83, v193, s[94:95]
	v_add_u32_e32 v161, 0xffffffe2, v102
	v_add_u32_e32 v162, 0xffffffe1, v102
	v_cmp_gt_u32_e32 vcc, s91, v161
	v_cmp_gt_u32_e64 s[92:93], s91, v162
	s_nop 0
	v_cndmask_b32_e32 v230, v83, v194, vcc
	v_cndmask_b32_e64 v231, v83, v195, s[92:93]
	v_max3_f32 v200, v200, v201, v202
	v_max3_f32 v203, v203, v204, v205
	v_max3_f32 v206, v206, v207, v208
	v_max3_f32 v209, v209, v210, v211
	v_max3_f32 v212, v212, v213, v214
	v_max3_f32 v215, v215, v216, v217
	v_max3_f32 v218, v218, v219, v220
	v_max3_f32 v221, v221, v222, v223
	v_max3_f32 v224, v224, v225, v226
	v_max3_f32 v227, v227, v228, v229
	v_max_f32_e32 v230, v230, v231
	v_max3_f32 v200, v200, v203, v206
	v_max3_f32 v209, v209, v212, v215
	v_max3_f32 v218, v218, v221, v224
	v_max_f32_e32 v227, v227, v230
	v_max3_f32 v200, v200, v209, v218
	v_max_f32_e32 v200, v200, v227
	v_mov_b32_e32 v82, v200
	s_branch .Lswa_tdone_0

; template <int DH, int MODE>
; __device__ void attn_item(const Params& p, int layer, int b, int blk, int head, char* smem) {
;     ...
;         tmax = fmaxf(tmax, __shfl_xor(tmax, 1));
;         float m_new = fmaxf(m_run, tmax);
;         float alpha = __builtin_amdgcn_exp2f(m_run - m_new);
;         float psum = 0.f;
; #pragma unroll 2
;         for (int s8 = 0; s8 < 4; ++s8) {
;           float4 va = s4[2 * s8], vb = s4[2 * s8 + 1];
;           float e[8] = {va.x, va.y, va.z, va.w, vb.x, vb.y, vb.z, vb.w};
;           float pv[8];
; #pragma unroll
;           for (int k = 0; k < 8; ++k) {
;             int kj = kjb + s8 * 8 + k;
;             bool valid = (kj > row) && (kj <= row + 128);
;             float pe = valid ? __builtin_amdgcn_exp2f(e[k] - m_new) : 0.f;
;             pv[k] = pe;
;             psum += pe;
;           }
.Lswa_tdone_0:
	v_cmp_lt_i32_e32 vcc, v157, v158
	s_mov_b32 s83, 0
	v_mov_b32_e32 v103, 0
	v_cndmask_b32_e32 v83, v156, v157, vcc
	v_lshlrev_b32_e32 v83, 2, v83
	ds_bpermute_b32 v101, v83, v82
	v_mov_b32_e32 v102, v91
	s_waitcnt lgkmcnt(0)
	v_max3_f32 v82, v87, v82, v101
	v_mov_b32_e32 v101, v93
	s_movk_i32 s91, 0x80
	v_sub_u32_e32 v112, v80, v92
	v_add_u32_e32 v113, -31, v112
	v_cmp_gt_u32_e32 vcc, 0x61, v113
	s_cmp_eq_u64 vcc, exec
	s_cbranch_scc1 .Lswa_pfast_0
	v_sub_f32_e32 v164, v164, v82
	v_sub_f32_e32 v165, v165, v82
	v_sub_f32_e32 v166, v166, v82
	v_exp_f32_e32 v164, v164
	v_exp_f32_e32 v165, v165
	v_exp_f32_e32 v166, v166
	v_mov_b32_e32 v196, v112
	v_add_u32_e32 v197, -1, v112
	v_add_u32_e32 v198, -2, v112
	v_cmp_gt_u32_e32 vcc, s91, v196
	v_cmp_gt_u32_e64 s[92:93], s91, v197
	v_cmp_gt_u32_e64 s[94:95], s91, v198
	v_cndmask_b32_e32 v164, 0, v164, vcc
	v_cndmask_b32_e64 v165, 0, v165, s[92:93]
	v_cndmask_b32_e64 v166, 0, v166, s[94:95]
	v_add_f32_e32 v103, v103, v164
	v_add_f32_e32 v103, v103, v165
	v_add_f32_e32 v103, v103, v166
	v_sub_f32_e32 v167, v167, v82
	v_sub_f32_e32 v168, v168, v82
	v_sub_f32_e32 v169, v169, v82
	v_exp_f32_e32 v167, v167
	v_exp_f32_e32 v168, v168
	v_exp_f32_e32 v169, v169
	v_add_u32_e32 v196, -3, v112
	v_add_u32_e32 v197, -4, v112
	v_add_u32_e32 v198, -5, v112
	v_cmp_gt_u32_e32 vcc, s91, v196
	v_cmp_gt_u32_e64 s[92:93], s91, v197
	v_cmp_gt_u32_e64 s[94:95], s91, v198
	v_cndmask_b32_e32 v167, 0, v167, vcc
	v_cndmask_b32_e64 v168, 0, v168, s[92:93]
	v_cndmask_b32_e64 v169, 0, v169, s[94:95]
	v_add_f32_e32 v103, v103, v167
	v_add_f32_e32 v103, v103, v168
	v_add_f32_e32 v103, v103, v169
	v_sub_f32_e32 v170, v170, v82
	v_sub_f32_e32 v171, v171, v82
	v_sub_f32_e32 v172, v172, v82
	v_exp_f32_e32 v170, v170
	v_exp_f32_e32 v171, v171
	v_exp_f32_e32 v172, v172
	v_add_u32_e32 v196, -6, v112
	v_add_u32_e32 v197, -7, v112
	v_add_u32_e32 v198, -8, v112
	v_cmp_gt_u32_e32 vcc, s91, v196
	v_cmp_gt_u32_e64 s[92:93], s91, v197
	v_cmp_gt_u32_e64 s[94:95], s91, v198
	v_cndmask_b32_e32 v170, 0, v170, vcc
	v_cndmask_b32_e64 v171, 0, v171, s[92:93]
	v_cndmask_b32_e64 v172, 0, v172, s[94:95]
	v_add_f32_e32 v103, v103, v170
	v_add_f32_e32 v103, v103, v171
	v_add_f32_e32 v103, v103, v172
	v_sub_f32_e32 v173, v173, v82
	v_sub_f32_e32 v174, v174, v82
	v_sub_f32_e32 v175, v175, v82
	v_exp_f32_e32 v173, v173
	v_exp_f32_e32 v174, v174
	v_exp_f32_e32 v175, v175
	v_add_u32_e32 v196, -9, v112
	v_add_u32_e32 v197, -10, v112
	v_add_u32_e32 v198, -11, v112
	v_cmp_gt_u32_e32 vcc, s91, v196
	v_cmp_gt_u32_e64 s[92:93], s91, v197
	v_cmp_gt_u32_e64 s[94:95], s91, v198
	v_cndmask_b32_e32 v173, 0, v173, vcc
	v_cndmask_b32_e64 v174, 0, v174, s[92:93]
	v_cndmask_b32_e64 v175, 0, v175, s[94:95]
	v_add_f32_e32 v103, v103, v173
	v_add_f32_e32 v103, v103, v174
	v_add_f32_e32 v103, v103, v175
	v_sub_f32_e32 v176, v176, v82
	v_sub_f32_e32 v177, v177, v82
	v_sub_f32_e32 v178, v178, v82
	v_exp_f32_e32 v176, v176
	v_exp_f32_e32 v177, v177
	v_exp_f32_e32 v178, v178
	v_add_u32_e32 v196, -12, v112
	v_add_u32_e32 v197, -13, v112
	v_add_u32_e32 v198, -14, v112
	v_cmp_gt_u32_e32 vcc, s91, v196
	v_cmp_gt_u32_e64 s[92:93], s91, v197
	v_cmp_gt_u32_e64 s[94:95], s91, v198
	v_cndmask_b32_e32 v176, 0, v176, vcc
	v_cndmask_b32_e64 v177, 0, v177, s[92:93]
	v_cndmask_b32_e64 v178, 0, v178, s[94:95]
	v_add_f32_e32 v103, v103, v176
	v_add_f32_e32 v103, v103, v177
	v_add_f32_e32 v103, v103, v178
	v_sub_f32_e32 v179, v179, v82
	v_sub_f32_e32 v180, v180, v82
	v_sub_f32_e32 v181, v181, v82
	v_exp_f32_e32 v179, v179
	v_exp_f32_e32 v180, v180
	v_exp_f32_e32 v181, v181
	v_add_u32_e32 v196, -15, v112
	v_add_u32_e32 v197, -16, v112
	v_add_u32_e32 v198, 0xffffffef, v112
	v_cmp_gt_u32_e32 vcc, s91, v196
	v_cmp_gt_u32_e64 s[92:93], s91, v197
	v_cmp_gt_u32_e64 s[94:95], s91, v198
	v_cndmask_b32_e32 v179, 0, v179, vcc
; __device__ __forceinline__ unsigned pack2(float a, float b) { return (unsigned)f2bf(a) | ((unsigned)f2bf(b) << 16); }
; template <int DH, int MODE>
; __device__ void attn_item(const Params& p, int layer, int b, int blk, int head, char* smem) {
;     ...
; #pragma unroll 2
;         for (int s8 = 0; s8 < 4; ++s8) {
;           float4 va = s4[2 * s8], vb = s4[2 * s8 + 1];
;           float e[8] = {va.x, va.y, va.z, va.w, vb.x, vb.y, vb.z, vb.w};
;           float pv[8];
; #pragma unroll
;           for (int k = 0; k < 8; ++k) {
;             int kj = kjb + s8 * 8 + k;
;             bool valid = (kj > row) && (kj <= row + 128);
;             float pe = valid ? __builtin_amdgcn_exp2f(e[k] - m_new) : 0.f;
;             pv[k] = pe;
;             psum += pe;
;           }
;           uint4 ov;
;           ov.x = pack2(pv[0], pv[1]); ov.y = pack2(pv[2], pv[3]);
;           ov.z = pack2(pv[4], pv[5]); ov.w = pack2(pv[6], pv[7]);
;           *reinterpret_cast<uint4*>(prow + s8 * 16) = ov;
;         }
	v_cndmask_b32_e64 v180, 0, v180, s[92:93]
	v_cndmask_b32_e64 v181, 0, v181, s[94:95]
	v_add_f32_e32 v103, v103, v179
	v_add_f32_e32 v103, v103, v180
	v_add_f32_e32 v103, v103, v181
	v_sub_f32_e32 v182, v182, v82
	v_sub_f32_e32 v183, v183, v82
	v_sub_f32_e32 v184, v184, v82
	v_exp_f32_e32 v182, v182
	v_exp_f32_e32 v183, v183
	v_exp_f32_e32 v184, v184
	v_add_u32_e32 v196, 0xffffffee, v112
	v_add_u32_e32 v197, 0xffffffed, v112
	v_add_u32_e32 v198, 0xffffffec, v112
	v_cmp_gt_u32_e32 vcc, s91, v196
	v_cmp_gt_u32_e64 s[92:93], s91, v197
	v_cmp_gt_u32_e64 s[94:95], s91, v198
	v_cndmask_b32_e32 v182, 0, v182, vcc
	v_cndmask_b32_e64 v183, 0, v183, s[92:93]
	v_cndmask_b32_e64 v184, 0, v184, s[94:95]
	v_add_f32_e32 v103, v103, v182
	v_add_f32_e32 v103, v103, v183
	v_add_f32_e32 v103, v103, v184
	v_sub_f32_e32 v185, v185, v82
	v_sub_f32_e32 v186, v186, v82
	v_sub_f32_e32 v187, v187, v82
	v_exp_f32_e32 v185, v185
	v_exp_f32_e32 v186, v186
	v_exp_f32_e32 v187, v187
	v_add_u32_e32 v196, 0xffffffeb, v112
	v_add_u32_e32 v197, 0xffffffea, v112
	v_add_u32_e32 v198, 0xffffffe9, v112
	v_cmp_gt_u32_e32 vcc, s91, v196
	v_cmp_gt_u32_e64 s[92:93], s91, v197
	v_cmp_gt_u32_e64 s[94:95], s91, v198
	v_cndmask_b32_e32 v185, 0, v185, vcc
	v_cndmask_b32_e64 v186, 0, v186, s[92:93]
	v_cndmask_b32_e64 v187, 0, v187, s[94:95]
	v_add_f32_e32 v103, v103, v185
	v_add_f32_e32 v103, v103, v186
	v_add_f32_e32 v103, v103, v187
	v_sub_f32_e32 v188, v188, v82
	v_sub_f32_e32 v189, v189, v82
	v_sub_f32_e32 v190, v190, v82
	v_exp_f32_e32 v188, v188
	v_exp_f32_e32 v189, v189
	v_exp_f32_e32 v190, v190
	v_add_u32_e32 v196, 0xffffffe8, v112
	v_add_u32_e32 v197, 0xffffffe7, v112
	v_add_u32_e32 v198, 0xffffffe6, v112
	v_cmp_gt_u32_e32 vcc, s91, v196
	v_cmp_gt_u32_e64 s[92:93], s91, v197
	v_cmp_gt_u32_e64 s[94:95], s91, v198
	v_cndmask_b32_e32 v188, 0, v188, vcc
	v_cndmask_b32_e64 v189, 0, v189, s[92:93]
	v_cndmask_b32_e64 v190, 0, v190, s[94:95]
	v_add_f32_e32 v103, v103, v188
	v_add_f32_e32 v103, v103, v189
	v_add_f32_e32 v103, v103, v190
	v_sub_f32_e32 v191, v191, v82
	v_sub_f32_e32 v192, v192, v82
	v_sub_f32_e32 v193, v193, v82
	v_exp_f32_e32 v191, v191
	v_exp_f32_e32 v192, v192
	v_exp_f32_e32 v193, v193
	v_add_u32_e32 v196, 0xffffffe5, v112
	v_add_u32_e32 v197, 0xffffffe4, v112
	v_add_u32_e32 v198, 0xffffffe3, v112
	v_cmp_gt_u32_e32 vcc, s91, v196
	v_cmp_gt_u32_e64 s[92:93], s91, v197
	v_cmp_gt_u32_e64 s[94:95], s91, v198
	v_cndmask_b32_e32 v191, 0, v191, vcc
	v_cndmask_b32_e64 v192, 0, v192, s[92:93]
	v_cndmask_b32_e64 v193, 0, v193, s[94:95]
	v_add_f32_e32 v103, v103, v191
	v_add_f32_e32 v103, v103, v192
	v_add_f32_e32 v103, v103, v193
	v_sub_f32_e32 v194, v194, v82
	v_sub_f32_e32 v195, v195, v82
	v_exp_f32_e32 v194, v194
	v_exp_f32_e32 v195, v195
	v_add_u32_e32 v196, 0xffffffe2, v112
	v_add_u32_e32 v197, 0xffffffe1, v112
	v_cmp_gt_u32_e32 vcc, s91, v196
	v_cmp_gt_u32_e64 s[92:93], s91, v197
	s_nop 0
	v_cndmask_b32_e32 v194, 0, v194, vcc
	v_cndmask_b32_e64 v195, 0, v195, s[92:93]
	v_add_f32_e32 v103, v103, v194
	v_add_f32_e32 v103, v103, v195
	v_cvt_pk_bf16_f32 v104, v164, v165
	v_cvt_pk_bf16_f32 v105, v166, v167
	v_cvt_pk_bf16_f32 v106, v168, v169
	v_cvt_pk_bf16_f32 v107, v170, v171
	ds_write_b128 v101, v[104:107]
	s_nop 0
	v_cvt_pk_bf16_f32 v104, v172, v173
	v_cvt_pk_bf16_f32 v105, v174, v175
	v_cvt_pk_bf16_f32 v106, v176, v177
	v_cvt_pk_bf16_f32 v107, v178, v179
	ds_write_b128 v101, v[104:107] offset:16
	s_nop 0
	v_cvt_pk_bf16_f32 v104, v180, v181
	v_cvt_pk_bf16_f32 v105, v182, v183
	v_cvt_pk_bf16_f32 v106, v184, v185
	v_cvt_pk_bf16_f32 v107, v186, v187
	ds_write_b128 v101, v[104:107] offset:32
	s_nop 0
	v_cvt_pk_bf16_f32 v104, v188, v189
	v_cvt_pk_bf16_f32 v105, v190, v191
	v_cvt_pk_bf16_f32 v106, v192, v193
	v_cvt_pk_bf16_f32 v107, v194, v195
	ds_write_b128 v101, v[104:107] offset:48
	s_branch .Lswa_pdone_0
